# v18 + MICROARCH item 9 stagger: waves 4-7 sleep 512 cycles at the start of each attention compute section so SIMD partners interleave MFMA and VALU phases
# speedup vs baseline: 1.0031x; 1.0031x over previous
; __device__ __forceinline__ f32x4 mfma16(bf16x8 a, bf16x8 b, f32x4 c) { return __builtin_amdgcn_mfma_f32_16x16x32_bf16(a, b, c, 0, 0, 0); }
; #define AT_LOADQ(T) do { const size_t tq_ = (T).tb + (size_t)(128 * (T).n + qi) * (T).d; \
;         _Pragma("unroll") for (int k4_ = 0; k4_ < 4; ++k4_) qf[k4_] = *(const bf16x8*)(AQ + tq_ * ATW + (T).head * 128 + k4_ * 32 + 8 * fq); qs = HS[tq_ * 24 + (T).head]; } while (0)
; __device__ __forceinline__ void attn_phase(int wv, const Args& a, LAS unsigned char* lds, int w, bool dmy) {
;     ...
;         if (it < 11) { T = attn_decode(12 * w + it + 1);
;             AT_LOADBLK(T, T.n); AT_LOADQ(T); }
;         const int px = (sl ^ 1) << 3;
;         const int lo2 = (wid & ~1) < 6 ? (wid & ~1) : 6;
;         f32x4 sT[10];
;         float mx = -INFINITY;
; #pragma unroll
;         for (int i = 0; i < 10; ++i) {
;             const int kt = lo2 + i, pkt = kt ^ px;
;             f32x4 ac = (f32x4){0.f, 0.f, 0.f, 0.f};
; #pragma unroll
;             for (int k4 = 0; k4 < 4; ++k4) ac = mfma16(lds_ld16(lds + AT_K + ((pkt * 16 + fr) * 136 + k4 * 32 + 8 * fq) * 2), qc[k4], ac);
.LBB0_657:
	v_readlane_b32 s6, v252, 1
	s_cmp_lt_u32 s6, 0x100
	s_cbranch_scc1 .Lat_nostag
	s_sleep 8
